# MoE last-round row-half split, XCD-aligned assignment (halves of unit u on workgroups u and u+128, whole units keep c = u mod 8)
# baseline (speedup 1.0000x reference)
.LBB0_1733:
	s_add_i32 s68, s68, 1
	s_mul_i32 s4, s68, s74
	s_mul_hi_u32 s5, s68, s3
	s_add_i32 s5, s5, s4
	s_mul_i32 s4, s68, s3
	s_add_u32 s8, s4, s2
	s_addc_u32 s9, s5, s57
	s_mov_b32 s91, 3
	s_cmp_eq_u32 s68, s93
	s_cbranch_scc0 .Lts_done_a
	s_mov_b32 s96, s2
	s_cmp_lt_u32 s2, s95
	s_cbranch_scc0 .Lts_c2_a
	s_mov_b32 s91, 1
	s_branch .Lts_set_a
.Lts_c2_a:
	s_cmp_lt_u32 s2, 0x80
	s_cbranch_scc1 .Lts_chk_a
	s_add_i32 s97, s95, 0x80
	s_cmp_lt_u32 s2, s97
	s_cbranch_scc0 .Lts_c4_a
	s_mov_b32 s91, 2
	s_sub_i32 s96, s2, 0x80
	s_branch .Lts_set_a

.Lts_chk_a:
	s_cmp_lt_u32 s96, s94
	s_cbranch_scc1 .Lts_set_a
	s_mov_b32 s8, s92
	s_branch .Lts_done_a

.LBB0_1821:
	s_add_i32 s57, s57, 1
	s_mul_i32 s4, s57, s61
	s_mul_hi_u32 s5, s57, s3
	s_add_i32 s5, s5, s4
	s_mul_i32 s4, s57, s3
	s_add_u32 s44, s4, s2
	s_addc_u32 s45, s5, s49
	s_mov_b32 s91, 3
	s_cmp_eq_u32 s57, s93
	s_cbranch_scc0 .Lts_done_b
	s_mov_b32 s96, s2
	s_cmp_lt_u32 s2, s95
	s_cbranch_scc0 .Lts_c2_b
	s_mov_b32 s91, 1
	s_branch .Lts_set_b

.Lts_chk_b:
	s_cmp_lt_u32 s96, s94
	s_cbranch_scc1 .Lts_set_b
	s_mov_b32 s44, s92
	s_branch .Lts_done_b
